# hgB step loop: q/z rows by 4 LDS-DMA loads a full step ahead into a wave-private 2-slot LDS ring (gates read ds_read_u16), V and merge loads hoisted to the step top; on top of GEMM boundary trims
# speedup vs baseline: 1.0142x; 1.0072x over previous
.LBB0_194:
	s_lshl_b32 s100, s6, 13
	s_add_i32 s100, s100, 0xe010
	v_writelane_b32 v235, s100, 0
	s_mulk_i32 s6, 0x1c00
	s_add_i32 s25, s6, 16
	s_lshl_b32 s6, s7, 12
	s_lshl_b32 s7, s38, 7
	s_or_b32 s54, s6, s7
	s_ashr_i32 s55, s54, 31
	s_add_u32 s2, s78, s2
	s_addc_u32 s3, s79, s3
	s_ashr_i32 s51, s50, 31
	s_lshl_b64 s[6:7], s[50:51], 1
	s_add_u32 s2, s2, s6
	s_addc_u32 s3, s3, s7
	s_or_b32 s42, s14, s54
	s_mul_i32 s38, s42, 0x1f00
	s_mul_hi_i32 s14, s42, 0x1f00
	s_add_u32 s38, s22, s38
	s_addc_u32 s14, s23, s14
	s_add_u32 s38, s38, s6
	s_addc_u32 s39, s14, s7
	v_and_b32_e32 v233, 63, v113
	v_lshrrev_b32_e32 v234, 3, v233
	v_and_b32_e32 v233, 7, v233
	v_sub_u32_e32 v236, 15, v234
	v_cndmask_b32_e64 v234, v236, v234, s[40:41]
	v_mul_u32_u24_e32 v234, 0x1f00, v234
	v_lshl_add_u32 v234, v233, 4, v234
	v_add_u32_e32 v236, 0xf800, v234
	v_subrev_u32_e32 v233, 0xf800, v234
	v_cndmask_b32_e64 v233, v233, v236, s[40:41]
	s_add_u32 s100, s38, 0x1500
	s_addc_u32 s101, s39, 0
	v_readlane_b32 vcc_lo, v235, 0
	s_nop 3
	s_mov_b32 m0, vcc_lo
	s_nop 0
	global_load_lds_dwordx4 v234, s[100:101]
	s_add_i32 m0, vcc_lo, 0x400
	s_nop 0
	global_load_lds_dwordx4 v233, s[100:101]
	s_cmp_eq_u32 s16, 0
	s_movk_i32 vcc_hi, 0x400
	s_cselect_b32 vcc_hi, 0x200, vcc_hi
	s_add_u32 s100, s100, vcc_hi
	s_addc_u32 s101, s101, 0
	s_add_i32 m0, vcc_lo, 0x800
	s_nop 0
	global_load_lds_dwordx4 v234, s[100:101]
	s_add_i32 m0, vcc_lo, 0xc00
	s_nop 0
	global_load_lds_dwordx4 v233, s[100:101]
	s_sub_u32 s100, s100, vcc_hi
	s_subb_u32 s101, s101, 0
	v_lshlrev_b32_e32 v128, 1, v64
	s_lshl_b32 s96, s12, 1
	s_mul_i32 s12, s26, 0xf80
	v_lshl_add_u64 v[70:71], s[38:39], 0, v[128:129]
	s_lshl_b32 s38, s12, 1
	s_mov_b32 s39, s97
	v_lshl_add_u64 v[72:73], v[70:71], 0, s[96:97]
	v_lshl_add_u64 v[74:75], v[70:71], 0, s[38:39]
	s_mul_i32 s14, s27, 0xf80
	v_add_co_u32_e32 v74, vcc, s86, v74
	v_lshl_add_u64 v[76:77], v[72:73], 0, s[38:39]
	s_lshl_b32 s38, s14, 1
	v_addc_co_u32_e32 v75, vcc, 0, v75, vcc
	v_lshl_add_u64 v[78:79], v[70:71], 0, s[38:39]
	v_lshl_add_u64 v[80:81], v[72:73], 0, s[38:39]
	s_mul_i32 s38, s37, 0xf80
	v_add_co_u32_e32 v78, vcc, s86, v78
	s_lshl_b32 s44, s38, 1
	s_mov_b32 s45, s97
	v_addc_co_u32_e32 v79, vcc, 0, v79, vcc
	v_lshl_add_u64 v[82:83], v[70:71], 0, s[44:45]
	s_mul_i32 s39, s36, 0xf80
	v_add_co_u32_e32 v82, vcc, s86, v82
	v_lshl_add_u64 v[84:85], v[72:73], 0, s[44:45]
	s_lshl_b32 s44, s39, 1
	v_addc_co_u32_e32 v83, vcc, 0, v83, vcc
	v_lshl_add_u64 v[86:87], v[70:71], 0, s[44:45]
	s_mul_i32 s53, s35, 0xf80
	v_add_co_u32_e32 v86, vcc, s86, v86
	v_lshl_add_u64 v[88:89], v[72:73], 0, s[44:45]
	s_lshl_b32 s44, s53, 1
	v_addc_co_u32_e32 v87, vcc, 0, v87, vcc
	v_lshl_add_u64 v[74:75], v[70:71], 0, s[44:45]
	s_mul_i32 s57, s29, 0xf80
	v_add_co_u32_e32 v74, vcc, s86, v74
	v_lshl_add_u64 v[76:77], v[72:73], 0, s[44:45]
	s_lshl_b32 s44, s57, 1
	v_addc_co_u32_e32 v75, vcc, 0, v75, vcc
	v_lshl_add_u64 v[78:79], v[70:71], 0, s[44:45]
	s_mul_i32 s59, s28, 0xf80
	v_add_co_u32_e32 v78, vcc, s86, v78
	v_lshl_add_u64 v[80:81], v[72:73], 0, s[44:45]
	s_lshl_b32 s44, s59, 1
	s_add_i32 s43, s16, 7
	v_addc_co_u32_e32 v79, vcc, 0, v79, vcc
	v_lshl_add_u64 v[82:83], v[70:71], 0, s[44:45]
	s_mul_i32 s60, s43, 0xf80
	v_add_co_u32_e32 v82, vcc, s86, v82
	v_lshl_add_u64 v[84:85], v[72:73], 0, s[44:45]
	s_lshl_b32 s44, s60, 1
	s_sub_i32 s16, 8, s16
	v_addc_co_u32_e32 v83, vcc, 0, v83, vcc
	v_lshl_add_u64 v[86:87], v[70:71], 0, s[44:45]
	s_mul_i32 s61, s16, 0xf80
	v_add_co_u32_e32 v86, vcc, s86, v86
	v_lshl_add_u64 v[88:89], v[72:73], 0, s[44:45]
	s_lshl_b32 s44, s61, 1
	v_addc_co_u32_e32 v87, vcc, 0, v87, vcc
	v_lshl_add_u64 v[74:75], v[70:71], 0, s[44:45]
	s_mul_i32 s62, s34, 0xf80
	v_add_co_u32_e32 v74, vcc, s86, v74
	v_lshl_add_u64 v[76:77], v[72:73], 0, s[44:45]
	s_lshl_b32 s44, s62, 1
	v_addc_co_u32_e32 v75, vcc, 0, v75, vcc
	v_lshl_add_u64 v[78:79], v[70:71], 0, s[44:45]
	s_mul_i32 s63, s24, 0xf80
	v_add_co_u32_e32 v78, vcc, s86, v78
	v_lshl_add_u64 v[80:81], v[72:73], 0, s[44:45]
	s_lshl_b32 s44, s63, 1
	v_addc_co_u32_e32 v79, vcc, 0, v79, vcc
	v_lshl_add_u64 v[82:83], v[70:71], 0, s[44:45]
	s_mul_i32 s80, s15, 0xf80
	v_add_co_u32_e32 v82, vcc, s86, v82
	v_lshl_add_u64 v[84:85], v[72:73], 0, s[44:45]
	s_lshl_b32 s44, s80, 1
	v_addc_co_u32_e32 v83, vcc, 0, v83, vcc
	v_lshl_add_u64 v[86:87], v[70:71], 0, s[44:45]
	s_mul_i32 s81, s21, 0xf80
	v_add_co_u32_e32 v86, vcc, s86, v86
	v_lshl_add_u64 v[88:89], v[72:73], 0, s[44:45]
	s_lshl_b32 s44, s81, 1
	v_addc_co_u32_e32 v87, vcc, 0, v87, vcc
	v_lshl_add_u64 v[74:75], v[70:71], 0, s[44:45]
	s_mul_i32 s94, s20, 0xf80
	v_add_co_u32_e32 v74, vcc, s86, v74
	v_lshl_add_u64 v[76:77], v[72:73], 0, s[44:45]
	s_lshl_b32 s44, s94, 1
	v_addc_co_u32_e32 v75, vcc, 0, v75, vcc
	v_lshl_add_u64 v[78:79], v[70:71], 0, s[44:45]
	s_mul_i32 s92, s17, 0xf80
	v_add_co_u32_e32 v78, vcc, s86, v78
	v_lshl_add_u64 v[80:81], v[72:73], 0, s[44:45]
	s_lshl_b32 s44, s92, 1
	v_addc_co_u32_e32 v79, vcc, 0, v79, vcc
	v_lshl_add_u64 v[82:83], v[70:71], 0, s[44:45]
	s_mul_i32 s82, s13, 0xf80
	v_add_co_u32_e32 v82, vcc, s86, v82
	v_lshl_add_u64 v[84:85], v[72:73], 0, s[44:45]
	s_lshl_b32 s44, s82, 1
	v_addc_co_u32_e32 v83, vcc, 0, v83, vcc
	v_lshl_add_u64 v[70:71], v[70:71], 0, s[44:45]
	v_add_co_u32_e32 v70, vcc, s86, v70
	v_lshl_add_u64 v[72:73], v[72:73], 0, s[44:45]
	s_nop 0
	v_addc_co_u32_e32 v71, vcc, 0, v71, vcc
	v_lshrrev_b32_e32 v112, 2, v64
	v_or_b32_e32 v72, s42, v112
	v_mov_b64_e32 v[70:71], s[22:23]
	v_mad_i64_i32 v[70:71], s[44:45], v72, s93, v[70:71]
	v_lshlrev_b32_e32 v72, 4, v113
	v_and_b32_e32 v72, 48, v72
	v_lshl_add_u64 v[70:71], v[70:71], 0, s[6:7]
	v_lshlrev_b32_e32 v74, 1, v72
	v_mov_b32_e32 v75, v129
	v_lshl_add_u64 v[70:71], v[70:71], 0, v[74:75]
	s_mov_b64 s[44:45], 0x1b00
	v_lshl_add_u64 v[80:81], v[70:71], 0, s[44:45]
	v_add_co_u32_e32 v70, vcc, s86, v70
	s_add_u32 s6, s22, s6
	s_nop 0
	v_addc_co_u32_e32 v71, vcc, 0, v71, vcc
	global_load_dwordx4 v[76:79], v[70:71], off offset:2816
	s_nop 0
	global_load_dwordx4 v[80:83], v[80:81], off offset:16
	v_mul_u32_u24_e32 v70, 0x90, v112
	s_addc_u32 s7, s23, s7
	v_mul_u32_u24_e32 v71, 0x48, v135
	v_add3_u32 v157, s25, v70, v74
	v_mov_b32_e32 v70, s25
	v_lshl_add_u64 v[114:115], s[6:7], 0, v[128:129]
	v_lshlrev_b32_e32 v71, 1, v71
	v_lshlrev_b32_e32 v73, 3, v69
	v_lshlrev_b32_e32 v69, 4, v69
	s_movk_i32 s6, 0x90
	v_add3_u32 v161, s25, v71, v69
	v_mad_u32_u24 v69, v135, s6, v70
	v_lshrrev_b32_e32 v70, 2, v135
	v_or_b32_e32 v70, v67, v70
	v_lshlrev_b32_e32 v71, 3, v135
	v_lshlrev_b32_e32 v128, 1, v67
	v_mul_u32_u24_e32 v70, 0x90, v70
	v_and_b32_e32 v71, 24, v71
	v_lshl_add_u64 v[116:117], s[2:3], 0, v[128:129]
	s_mul_i32 s2, s26, 0x48
	v_add3_u32 v163, s25, v70, v71
	v_add_u32_e32 v71, s2, v64
	s_mul_i32 s2, s27, 0x48
	v_lshl_add_u32 v164, v71, 1, s25
	v_add_u32_e32 v71, s2, v64
	s_mul_i32 s2, s37, 0x48
	v_lshl_add_u32 v165, v71, 1, s25
	v_add_u32_e32 v71, s2, v64
	s_mul_i32 s2, s36, 0x48
	v_lshl_add_u32 v166, v71, 1, s25
	v_add_u32_e32 v71, s2, v64
	s_mul_i32 s2, s35, 0x48
	v_lshl_add_u32 v167, v71, 1, s25
	v_add_u32_e32 v71, s2, v64
	s_mul_i32 s2, s29, 0x48
	v_lshl_add_u32 v168, v71, 1, s25
	v_add_u32_e32 v71, s2, v64
	s_mul_i32 s2, s28, 0x48
	v_lshl_add_u32 v170, v71, 1, s25
	v_add_u32_e32 v71, s2, v64
	s_mulk_i32 s43, 0x48
	v_lshl_add_u32 v171, v71, 1, s25
	v_add_u32_e32 v71, s43, v64
	s_mulk_i32 s16, 0x48
	v_lshl_add_u32 v172, v71, 1, s25
	v_add_u32_e32 v71, s16, v64
	s_mul_i32 s2, s34, 0x48
	v_lshl_add_u32 v173, v71, 1, s25
	v_add_u32_e32 v71, s2, v64
	s_mul_i32 s2, s24, 0x48
	v_lshl_add_u32 v174, v71, 1, s25
	v_add_u32_e32 v71, s2, v64
	s_mul_i32 s2, s15, 0x48
	v_lshl_add_u32 v175, v71, 1, s25
	v_add_u32_e32 v71, s2, v64
	s_mul_i32 s2, s21, 0x48
	v_lshl_add_u32 v176, v71, 1, s25
	v_add_u32_e32 v71, s2, v64
	s_mul_i32 s2, s20, 0x48
	v_lshl_add_u32 v177, v71, 1, s25
	v_add_u32_e32 v71, s2, v64
	s_mul_i32 s2, s17, 0x48
	v_lshl_add_u32 v178, v71, 1, s25
	v_add_u32_e32 v71, s2, v64
	s_mul_i32 s2, s13, 0x48
	v_lshl_add_u32 v160, v64, 2, s25
	v_add_u32_e32 v64, s2, v64
	v_cmp_le_u32_e32 vcc, v67, v135
	v_lshl_add_u32 v180, v64, 1, s25
	v_lshl_add_u32 v179, v71, 1, s25
	v_cndmask_b32_e64 v64, 0, 1, vcc
	v_cmp_ge_u32_e32 vcc, v67, v135
	v_and_b32_e32 v70, 48, v113
	s_waitcnt vmcnt(0)
	v_sub_f32_e32 v158, 1.0, v137
	v_cndmask_b32_e64 v71, 0, 1, vcc
	v_cndmask_b32_e64 v64, v71, v64, s[40:41]
	v_and_b32_e32 v64, 1, v64
	v_cmp_lt_u32_e32 vcc, v67, v135
	v_cmp_eq_u32_e64 s[42:43], 1, v64
	s_lshl_b32 s56, s12, 1
	v_cndmask_b32_e64 v64, 0, 1, vcc
	v_cmp_ge_u32_e32 vcc, v68, v135
	s_lshl_b32 s58, s14, 1
	s_lshl_b32 s16, s38, 1
	v_cndmask_b32_e64 v67, 0, 1, vcc
	v_cndmask_b32_e64 v64, v67, v64, s[40:41]
	v_and_b32_e32 v64, 1, v64
	v_cmp_le_u32_e32 vcc, v66, v135
	v_cmp_eq_u32_e64 s[44:45], 1, v64
	s_lshl_b32 s28, s39, 1
	v_cndmask_b32_e64 v64, 0, 1, vcc
	v_cmp_ge_u32_e32 vcc, v66, v135
	s_lshl_b32 s26, s53, 1
	s_lshl_b32 s20, s57, 1
	v_cndmask_b32_e64 v66, 0, 1, vcc
	v_cndmask_b32_e64 v64, v66, v64, s[40:41]
	v_and_b32_e32 v64, 1, v64
	v_cmp_le_u32_e32 vcc, v65, v135
	v_cmp_eq_u32_e64 s[46:47], 1, v64
	s_lshl_b32 s38, s59, 1
	v_cndmask_b32_e64 v64, 0, 1, vcc
	v_cmp_ge_u32_e32 vcc, v65, v135
	s_lshl_b32 s6, s60, 1
	s_lshl_b32 s60, s61, 1
	v_cndmask_b32_e64 v65, 0, 1, vcc
	v_cndmask_b32_e64 v64, v65, v64, s[40:41]
	v_and_b32_e32 v64, 1, v64
	v_cmp_eq_u32_e64 s[48:49], 1, v64
	s_lshl_b32 s34, s62, 1
	s_lshl_b32 s62, s63, 1
	s_lshl_b32 s24, s80, 1
	s_lshl_b32 s2, s81, 1
	s_lshl_b32 s36, s94, 1
	s_lshl_b32 s14, s92, 1
	s_lshl_b32 s12, s82, 1
	v_lshlrev_b32_e32 v118, 1, v72
	v_add_u32_e32 v184, v69, v73
	v_add_u32_e32 v185, s25, v70
	v_mov_b32_e32 v186, v113
	v_readlane_b32 s92, v255, 22
	s_movk_i32 s94, 0xf80
	s_and_b64 vcc, s[40:41], exec
	s_movk_i32 s14, 0x400
	s_cselect_b32 s14, 0x200, s14
	s_mov_b32 s16, 0xfffe1000
	s_cselect_b32 s16, 0x1f000, s16
	s_cselect_b32 s17, 0, -1
	s_add_u32 s12, s100, s16
	s_addc_u32 s13, s101, s17
	v_readlane_b32 s20, v235, 0
	v_and_b32_e32 v237, 63, v113
	s_nop 1
	v_lshl_add_u32 v237, v237, 1, s20
	s_branch .LBB0_196
.LBB0_195:
	s_add_i32 s88, s88, -1
	v_pk_mul_f32 v[2:3], v[98:99], v[2:3]
	v_pk_mul_f32 v[0:1], v[96:97], v[0:1]
	v_pk_mul_f32 v[6:7], v[98:99], v[6:7]
	v_pk_mul_f32 v[4:5], v[96:97], v[4:5]
	v_pk_mul_f32 v[10:11], v[98:99], v[10:11]
	v_pk_mul_f32 v[8:9], v[96:97], v[8:9]
	v_pk_mul_f32 v[14:15], v[98:99], v[14:15]
	v_pk_mul_f32 v[12:13], v[96:97], v[12:13]
	v_pk_mul_f32 v[18:19], v[102:103], v[18:19]
	v_pk_mul_f32 v[16:17], v[100:101], v[16:17]
	v_pk_mul_f32 v[22:23], v[102:103], v[22:23]
	v_pk_mul_f32 v[20:21], v[100:101], v[20:21]
	v_pk_mul_f32 v[34:35], v[102:103], v[34:35]
	v_pk_mul_f32 v[32:33], v[100:101], v[32:33]
	v_pk_mul_f32 v[38:39], v[102:103], v[38:39]
	v_pk_mul_f32 v[36:37], v[100:101], v[36:37]
	v_pk_mul_f32 v[26:27], v[110:111], v[26:27]
	v_pk_mul_f32 v[24:25], v[108:109], v[24:25]
	v_pk_mul_f32 v[30:31], v[110:111], v[30:31]
	v_pk_mul_f32 v[28:29], v[108:109], v[28:29]
	v_pk_mul_f32 v[42:43], v[110:111], v[42:43]
	v_pk_mul_f32 v[40:41], v[108:109], v[40:41]
	v_pk_mul_f32 v[46:47], v[110:111], v[46:47]
	v_pk_mul_f32 v[44:45], v[108:109], v[44:45]
	s_waitcnt lgkmcnt(0)
	v_pk_mul_f32 v[50:51], v[106:107], v[50:51]
	v_pk_mul_f32 v[48:49], v[104:105], v[48:49]
	v_pk_mul_f32 v[54:55], v[106:107], v[54:55]
	v_pk_mul_f32 v[52:53], v[104:105], v[52:53]
	v_pk_mul_f32 v[58:59], v[106:107], v[58:59]
	v_pk_mul_f32 v[56:57], v[104:105], v[56:57]
	v_pk_mul_f32 v[62:63], v[106:107], v[62:63]
	v_pk_mul_f32 v[60:61], v[104:105], v[60:61]
	v_add_u32_e32 v186, 0x200, v186
	v_xor_b32_e32 v237, 0x1000, v237
	s_cmp_lg_u32 s88, -2
	s_mov_b32 s91, s53
	s_cbranch_scc0 .LBB0_190
.LBB0_196:
	ds_write_b128 v157, v[76:79] offset:4608
	ds_write_b128 v157, v[80:83] offset:4624
	s_add_i32 s53, s91, 1
	v_add_co_u32_e64 v96, vcc, s88, 1
	ds_read_u16 v145, v237 offset:2048
	ds_read_u16 v144, v237 offset:0
	ds_read_u16 v147, v237 offset:2176
	ds_read_u16 v146, v237 offset:128
	ds_read_u16 v149, v237 offset:2304
	ds_read_u16 v148, v237 offset:256
	ds_read_u16 v151, v237 offset:2432
	ds_read_u16 v150, v237 offset:384
	ds_read_u16 v153, v237 offset:2560
	ds_read_u16 v152, v237 offset:512
	ds_read_u16 v155, v237 offset:2688
	ds_read_u16 v154, v237 offset:640
	ds_read_u16 v159, v237 offset:2816
	ds_read_u16 v156, v237 offset:768
	ds_read_u16 v169, v237 offset:2944
	ds_read_u16 v162, v237 offset:896
	s_cmp_eq_u32 s88, -1
	s_cbranch_scc1 .Lhg_noload
	s_and_b64 s[80:81], s[40:41], exec
	s_cselect_b32 s3, s53, s88
	s_lshl_b32 s3, s3, 4
	s_ashr_i32 s7, s3, 31
	s_add_u32 s81, s3, s54
	s_addc_u32 s80, s7, s55
	v_or_b32_e32 v78, s81, v112
	v_mov_b64_e32 v[76:77], s[22:23]
	v_mad_u64_u32 v[76:77], vcc, v78, s93, v[76:77]
	v_mad_i32_i24 v77, s80, v216, v77
	v_lshl_add_u64 v[76:77], s[50:51], 1, v[76:77]
	v_mov_b32_e32 v119, v129
	v_lshl_add_u64 v[76:77], v[76:77], 0, v[118:119]
	s_mov_b64 s[80:81], 0x1b00
	v_lshl_add_u64 v[80:81], v[76:77], 0, s[80:81]
	v_add_co_u32_e32 v76, vcc, 0x1000, v76
	s_nop 1
	v_addc_co_u32_e32 v77, vcc, 0, v77, vcc
	global_load_dwordx4 v[76:79], v[76:77], off offset:2816
	s_nop 0
	global_load_dwordx4 v[80:83], v[80:81], off offset:16
	s_xor_b32 s20, s20, 0x1000
	s_add_u32 s26, s12, s14
	s_addc_u32 s27, s13, 0
	s_mov_b32 m0, s20
	s_nop 0
	global_load_lds_dwordx4 v234, s[12:13]
	s_add_i32 m0, s20, 0x400
	s_nop 0
	global_load_lds_dwordx4 v233, s[12:13]
	s_add_i32 m0, s20, 0x800
	s_nop 0
	global_load_lds_dwordx4 v234, s[26:27]
	s_add_i32 m0, s20, 0xc00
	s_nop 0
	global_load_lds_dwordx4 v233, s[26:27]
	s_add_u32 s12, s12, s16
	s_addc_u32 s13, s13, s17
	s_mov_b32 s3, s97
	s_mov_b32 s7, s97

.Lhg_gates:
	s_waitcnt lgkmcnt(8)
	v_lshlrev_b32_e32 v228, 16, v145
	v_max_f32_e32 v228, v228, v228
	v_med3_f32 v228, v228, s85, v215
	v_mul_f32_e32 v228, 0xbfb8aa3b, v228
	v_exp_f32_e32 v228, v228
	s_nop 0
	v_add_f32_e32 v229, 1.0, v228
	v_rcp_f32_e32 v229, v229
	v_mul_f32_e32 v228, v158, v228
	v_fma_f32 v230, v158, v229, v137
	v_mul_f32_e32 v228, v228, v229
	v_lshlrev_b32_e32 v229, 16, v144
	v_mul_f32_e32 v231, 0xbfb8aa3b, v229
	v_exp_f32_e32 v231, v231
	s_nop 0
	v_add_f32_e32 v231, 1.0, v231
	v_rcp_f32_e32 v231, v231
	s_nop 0
	v_mul_f32_e32 v229, v231, v229
	v_mul_f32_e32 v229, v230, v229
	v_cvt_pk_bf16_f32 v229, v229, s0
	ds_write_b16 v164, v229
	v_max_f32_e32 v229, 0xda24260, v230
	v_rcp_f32_e32 v229, v229
	s_nop 0
	v_mul_f32_e32 v228, v228, v229
	v_cvt_pk_bf16_f32 v228, v228, s0
	ds_write_b16 v164, v228 offset:2304
	v_lshlrev_b32_e32 v228, 16, v147
	v_max_f32_e32 v228, v228, v228
	v_med3_f32 v228, v228, s85, v215
	v_mul_f32_e32 v228, 0xbfb8aa3b, v228
	v_exp_f32_e32 v228, v228
	s_nop 0
	v_add_f32_e32 v229, 1.0, v228
	v_rcp_f32_e32 v229, v229
	v_mul_f32_e32 v228, v158, v228
	v_fma_f32 v231, v158, v229, v137
	v_mul_f32_e32 v228, v228, v229
	v_lshlrev_b32_e32 v229, 16, v146
	v_mul_f32_e32 v232, 0xbfb8aa3b, v229
	v_exp_f32_e32 v232, v232
	v_mul_f32_e32 v230, v230, v231
	v_add_f32_e32 v232, 1.0, v232
	v_rcp_f32_e32 v232, v232
	s_nop 0
	v_mul_f32_e32 v229, v232, v229
	v_mul_f32_e32 v229, v230, v229
	v_cvt_pk_bf16_f32 v229, v229, s0
	ds_write_b16 v165, v229
	v_max_f32_e32 v229, 0xda24260, v230
	v_rcp_f32_e32 v229, v229
	s_nop 0
	v_mul_f32_e32 v228, v228, v229
	v_cvt_pk_bf16_f32 v228, v228, s0
	ds_write_b16 v165, v228 offset:2304
	v_lshlrev_b32_e32 v228, 16, v149
	v_max_f32_e32 v228, v228, v228
	v_med3_f32 v228, v228, s85, v215
	v_mul_f32_e32 v228, 0xbfb8aa3b, v228
	v_exp_f32_e32 v228, v228
	s_nop 0
	v_add_f32_e32 v229, 1.0, v228
	v_rcp_f32_e32 v229, v229
	v_mul_f32_e32 v228, v158, v228
	v_fma_f32 v231, v158, v229, v137
	v_mul_f32_e32 v228, v228, v229
	v_lshlrev_b32_e32 v229, 16, v148
	v_mul_f32_e32 v232, 0xbfb8aa3b, v229
	v_exp_f32_e32 v232, v232
	v_mul_f32_e32 v230, v230, v231
	v_add_f32_e32 v232, 1.0, v232
	v_rcp_f32_e32 v232, v232
	s_nop 0
	v_mul_f32_e32 v229, v232, v229
	v_mul_f32_e32 v229, v230, v229
	v_cvt_pk_bf16_f32 v229, v229, s0
	ds_write_b16 v166, v229
	v_max_f32_e32 v229, 0xda24260, v230
	v_rcp_f32_e32 v229, v229
	s_nop 0
	v_mul_f32_e32 v228, v228, v229
	v_cvt_pk_bf16_f32 v228, v228, s0
	ds_write_b16 v166, v228 offset:2304
	v_lshlrev_b32_e32 v228, 16, v151
	v_max_f32_e32 v228, v228, v228
	v_med3_f32 v228, v228, s85, v215
	v_mul_f32_e32 v228, 0xbfb8aa3b, v228
	v_exp_f32_e32 v228, v228
	s_nop 0
	v_add_f32_e32 v229, 1.0, v228
	v_rcp_f32_e32 v229, v229
	v_mul_f32_e32 v228, v158, v228
	v_fma_f32 v231, v158, v229, v137
	v_mul_f32_e32 v228, v228, v229
	v_lshlrev_b32_e32 v229, 16, v150
	v_mul_f32_e32 v232, 0xbfb8aa3b, v229
	v_exp_f32_e32 v232, v232
	v_mul_f32_e32 v230, v230, v231
	v_add_f32_e32 v232, 1.0, v232
	v_rcp_f32_e32 v232, v232
	s_nop 0
	v_mul_f32_e32 v229, v232, v229
	v_mul_f32_e32 v229, v230, v229
	v_cvt_pk_bf16_f32 v229, v229, s0
	ds_write_b16 v167, v229
	v_max_f32_e32 v229, 0xda24260, v230
	v_rcp_f32_e32 v229, v229
	s_nop 0
	v_mul_f32_e32 v228, v228, v229
	v_cvt_pk_bf16_f32 v228, v228, s0
	ds_write_b16 v167, v228 offset:2304
	ds_read_u16 v182, v237 offset:3072
	ds_read_u16 v181, v237 offset:1024
	ds_read_u16 v187, v237 offset:3200
	ds_read_u16 v183, v237 offset:1152
	ds_read_u16 v189, v237 offset:3328
	ds_read_u16 v188, v237 offset:1280
	ds_read_u16 v191, v237 offset:3456
	ds_read_u16 v190, v237 offset:1408
	s_waitcnt lgkmcnt(8)
	v_lshlrev_b32_e32 v228, 16, v153
	v_max_f32_e32 v228, v228, v228
	v_med3_f32 v228, v228, s85, v215
	v_mul_f32_e32 v228, 0xbfb8aa3b, v228
	v_exp_f32_e32 v228, v228
	s_nop 0
	v_add_f32_e32 v229, 1.0, v228
	v_rcp_f32_e32 v229, v229
	v_mul_f32_e32 v228, v158, v228
	v_fma_f32 v231, v158, v229, v137
	v_mul_f32_e32 v228, v228, v229
	v_lshlrev_b32_e32 v229, 16, v152
	v_mul_f32_e32 v232, 0xbfb8aa3b, v229
	v_exp_f32_e32 v232, v232
	v_mul_f32_e32 v230, v230, v231
	v_add_f32_e32 v232, 1.0, v232
	v_rcp_f32_e32 v232, v232
	s_nop 0
	v_mul_f32_e32 v229, v232, v229
	v_mul_f32_e32 v229, v230, v229
	v_cvt_pk_bf16_f32 v229, v229, s0
	ds_write_b16 v168, v229
	v_max_f32_e32 v229, 0xda24260, v230
	v_rcp_f32_e32 v229, v229
	s_nop 0
	v_mul_f32_e32 v228, v228, v229
	v_cvt_pk_bf16_f32 v228, v228, s0
	ds_write_b16 v168, v228 offset:2304
	v_lshlrev_b32_e32 v228, 16, v155
	v_max_f32_e32 v228, v228, v228
	v_med3_f32 v228, v228, s85, v215
	v_mul_f32_e32 v228, 0xbfb8aa3b, v228
	v_exp_f32_e32 v228, v228
	s_nop 0
	v_add_f32_e32 v229, 1.0, v228
	v_rcp_f32_e32 v229, v229
	v_mul_f32_e32 v228, v158, v228
	v_fma_f32 v231, v158, v229, v137
	v_mul_f32_e32 v228, v228, v229
	v_lshlrev_b32_e32 v229, 16, v154
	v_mul_f32_e32 v232, 0xbfb8aa3b, v229
	v_exp_f32_e32 v232, v232
	v_mul_f32_e32 v230, v230, v231
	v_add_f32_e32 v232, 1.0, v232
	v_rcp_f32_e32 v232, v232
	s_nop 0
	v_mul_f32_e32 v229, v232, v229
	v_mul_f32_e32 v229, v230, v229
	v_cvt_pk_bf16_f32 v229, v229, s0
	ds_write_b16 v170, v229
	v_max_f32_e32 v229, 0xda24260, v230
	v_rcp_f32_e32 v229, v229
	s_nop 0
	v_mul_f32_e32 v228, v228, v229
	v_cvt_pk_bf16_f32 v228, v228, s0
	ds_write_b16 v170, v228 offset:2304
	v_lshlrev_b32_e32 v228, 16, v159
	v_max_f32_e32 v228, v228, v228
	v_med3_f32 v228, v228, s85, v215
	v_mul_f32_e32 v228, 0xbfb8aa3b, v228
	v_exp_f32_e32 v228, v228
	s_nop 0
	v_add_f32_e32 v229, 1.0, v228
	v_rcp_f32_e32 v229, v229
	v_mul_f32_e32 v228, v158, v228
	v_fma_f32 v231, v158, v229, v137
	v_mul_f32_e32 v228, v228, v229
	v_lshlrev_b32_e32 v229, 16, v156
	v_mul_f32_e32 v232, 0xbfb8aa3b, v229
	v_exp_f32_e32 v232, v232
	v_mul_f32_e32 v230, v230, v231
	v_add_f32_e32 v232, 1.0, v232
	v_rcp_f32_e32 v232, v232
	s_nop 0
	v_mul_f32_e32 v229, v232, v229
	v_mul_f32_e32 v229, v230, v229
	v_cvt_pk_bf16_f32 v229, v229, s0
	ds_write_b16 v171, v229
	v_max_f32_e32 v229, 0xda24260, v230
	v_rcp_f32_e32 v229, v229
	s_nop 0
	v_mul_f32_e32 v228, v228, v229
	v_cvt_pk_bf16_f32 v228, v228, s0
	ds_write_b16 v171, v228 offset:2304
	v_lshlrev_b32_e32 v228, 16, v169
	v_max_f32_e32 v228, v228, v228
	v_med3_f32 v228, v228, s85, v215
	v_mul_f32_e32 v228, 0xbfb8aa3b, v228
	v_exp_f32_e32 v228, v228
	s_nop 0
	v_add_f32_e32 v229, 1.0, v228
	v_rcp_f32_e32 v229, v229
	v_mul_f32_e32 v228, v158, v228
	v_fma_f32 v231, v158, v229, v137
	v_mul_f32_e32 v228, v228, v229
	v_lshlrev_b32_e32 v229, 16, v162
	v_mul_f32_e32 v232, 0xbfb8aa3b, v229
	v_exp_f32_e32 v232, v232
	v_mul_f32_e32 v230, v230, v231
	v_add_f32_e32 v232, 1.0, v232
	v_rcp_f32_e32 v232, v232
	s_nop 0
	v_mul_f32_e32 v229, v232, v229
	v_mul_f32_e32 v229, v230, v229
	v_cvt_pk_bf16_f32 v229, v229, s0
	ds_write_b16 v172, v229
	v_max_f32_e32 v229, 0xda24260, v230
	v_rcp_f32_e32 v229, v229
	s_nop 0
	v_mul_f32_e32 v228, v228, v229
	v_cvt_pk_bf16_f32 v228, v228, s0
	ds_write_b16 v172, v228 offset:2304
	ds_read_u16 v196, v237 offset:3584
	ds_read_u16 v195, v237 offset:1536
	ds_read_u16 v198, v237 offset:3712
	ds_read_u16 v197, v237 offset:1664
	ds_read_u16 v220, v237 offset:3840
	ds_read_u16 v199, v237 offset:1792
	ds_read_u16 v222, v237 offset:3968
	ds_read_u16 v221, v237 offset:1920
	s_waitcnt lgkmcnt(8)
	v_lshlrev_b32_e32 v228, 16, v182
	v_max_f32_e32 v228, v228, v228
	v_med3_f32 v228, v228, s85, v215
	v_mul_f32_e32 v228, 0xbfb8aa3b, v228
	v_exp_f32_e32 v228, v228
	s_nop 0
	v_add_f32_e32 v229, 1.0, v228
	v_rcp_f32_e32 v229, v229
	v_mul_f32_e32 v228, v158, v228
	v_fma_f32 v231, v158, v229, v137
	v_mul_f32_e32 v228, v228, v229
	v_lshlrev_b32_e32 v229, 16, v181
	v_mul_f32_e32 v232, 0xbfb8aa3b, v229
	v_exp_f32_e32 v232, v232
	v_mul_f32_e32 v230, v230, v231
	v_add_f32_e32 v232, 1.0, v232
	v_rcp_f32_e32 v232, v232
	s_nop 0
	v_mul_f32_e32 v229, v232, v229
	v_mul_f32_e32 v229, v230, v229
	v_cvt_pk_bf16_f32 v229, v229, s0
	ds_write_b16 v173, v229
	v_max_f32_e32 v229, 0xda24260, v230
	v_rcp_f32_e32 v229, v229
	s_nop 0
	v_mul_f32_e32 v228, v228, v229
	v_cvt_pk_bf16_f32 v228, v228, s0
	ds_write_b16 v173, v228 offset:2304
	v_lshlrev_b32_e32 v228, 16, v187
	v_max_f32_e32 v228, v228, v228
	v_med3_f32 v228, v228, s85, v215
	v_mul_f32_e32 v228, 0xbfb8aa3b, v228
	v_exp_f32_e32 v228, v228
	s_nop 0
	v_add_f32_e32 v229, 1.0, v228
	v_rcp_f32_e32 v229, v229
	v_mul_f32_e32 v228, v158, v228
	v_fma_f32 v231, v158, v229, v137
	v_mul_f32_e32 v228, v228, v229
	v_lshlrev_b32_e32 v229, 16, v183
	v_mul_f32_e32 v232, 0xbfb8aa3b, v229
	v_exp_f32_e32 v232, v232
	v_mul_f32_e32 v230, v230, v231
	v_add_f32_e32 v232, 1.0, v232
	v_rcp_f32_e32 v232, v232
	s_nop 0
	v_mul_f32_e32 v229, v232, v229
	v_mul_f32_e32 v229, v230, v229
	v_cvt_pk_bf16_f32 v229, v229, s0
	ds_write_b16 v174, v229
	v_max_f32_e32 v229, 0xda24260, v230
	v_rcp_f32_e32 v229, v229
	s_nop 0
	v_mul_f32_e32 v228, v228, v229
	v_cvt_pk_bf16_f32 v228, v228, s0
	ds_write_b16 v174, v228 offset:2304
	v_lshlrev_b32_e32 v228, 16, v189
	v_max_f32_e32 v228, v228, v228
	v_med3_f32 v228, v228, s85, v215
	v_mul_f32_e32 v228, 0xbfb8aa3b, v228
	v_exp_f32_e32 v228, v228
	s_nop 0
	v_add_f32_e32 v229, 1.0, v228
	v_rcp_f32_e32 v229, v229
	v_mul_f32_e32 v228, v158, v228
	v_fma_f32 v231, v158, v229, v137
	v_mul_f32_e32 v228, v228, v229
	v_lshlrev_b32_e32 v229, 16, v188
	v_mul_f32_e32 v232, 0xbfb8aa3b, v229
	v_exp_f32_e32 v232, v232
	v_mul_f32_e32 v230, v230, v231
	v_add_f32_e32 v232, 1.0, v232
	v_rcp_f32_e32 v232, v232
	s_nop 0
	v_mul_f32_e32 v229, v232, v229
	v_mul_f32_e32 v229, v230, v229
	v_cvt_pk_bf16_f32 v229, v229, s0
	ds_write_b16 v175, v229
	v_max_f32_e32 v229, 0xda24260, v230
	v_rcp_f32_e32 v229, v229
	s_nop 0
	v_mul_f32_e32 v228, v228, v229
	v_cvt_pk_bf16_f32 v228, v228, s0
	ds_write_b16 v175, v228 offset:2304
	v_lshlrev_b32_e32 v228, 16, v191
	v_max_f32_e32 v228, v228, v228
	v_med3_f32 v228, v228, s85, v215
	v_mul_f32_e32 v228, 0xbfb8aa3b, v228
	v_exp_f32_e32 v228, v228
	s_nop 0
	v_add_f32_e32 v229, 1.0, v228
	v_rcp_f32_e32 v229, v229
	v_mul_f32_e32 v228, v158, v228
	v_fma_f32 v231, v158, v229, v137
	v_mul_f32_e32 v228, v228, v229
	v_lshlrev_b32_e32 v229, 16, v190
	v_mul_f32_e32 v232, 0xbfb8aa3b, v229
	v_exp_f32_e32 v232, v232
	v_mul_f32_e32 v230, v230, v231
	v_add_f32_e32 v232, 1.0, v232
	v_rcp_f32_e32 v232, v232
	s_nop 0
	v_mul_f32_e32 v229, v232, v229
	v_mul_f32_e32 v229, v230, v229
	v_cvt_pk_bf16_f32 v229, v229, s0
	ds_write_b16 v176, v229
	v_max_f32_e32 v229, 0xda24260, v230
	v_rcp_f32_e32 v229, v229
	s_nop 0
	v_mul_f32_e32 v228, v228, v229
	v_cvt_pk_bf16_f32 v228, v228, s0
	ds_write_b16 v176, v228 offset:2304
	s_waitcnt lgkmcnt(0)
	v_lshlrev_b32_e32 v228, 16, v196
	v_max_f32_e32 v228, v228, v228
	v_med3_f32 v228, v228, s85, v215
	v_mul_f32_e32 v228, 0xbfb8aa3b, v228
	v_exp_f32_e32 v228, v228
	s_nop 0
	v_add_f32_e32 v229, 1.0, v228
	v_rcp_f32_e32 v229, v229
	v_mul_f32_e32 v228, v158, v228
	v_fma_f32 v231, v158, v229, v137
	v_mul_f32_e32 v228, v228, v229
	v_lshlrev_b32_e32 v229, 16, v195
	v_mul_f32_e32 v232, 0xbfb8aa3b, v229
	v_exp_f32_e32 v232, v232
	v_mul_f32_e32 v230, v230, v231
	v_add_f32_e32 v232, 1.0, v232
	v_rcp_f32_e32 v232, v232
	s_nop 0
	v_mul_f32_e32 v229, v232, v229
	v_mul_f32_e32 v229, v230, v229
	v_cvt_pk_bf16_f32 v229, v229, s0
	ds_write_b16 v177, v229
	v_max_f32_e32 v229, 0xda24260, v230
	v_rcp_f32_e32 v229, v229
	s_nop 0
	v_mul_f32_e32 v228, v228, v229
	v_cvt_pk_bf16_f32 v228, v228, s0
	ds_write_b16 v177, v228 offset:2304
	v_lshlrev_b32_e32 v228, 16, v198
	v_max_f32_e32 v228, v228, v228
	v_med3_f32 v228, v228, s85, v215
	v_mul_f32_e32 v228, 0xbfb8aa3b, v228
	v_exp_f32_e32 v228, v228
	s_nop 0
	v_add_f32_e32 v229, 1.0, v228
	v_rcp_f32_e32 v229, v229
	v_mul_f32_e32 v228, v158, v228
	v_fma_f32 v231, v158, v229, v137
	v_mul_f32_e32 v228, v228, v229
	v_lshlrev_b32_e32 v229, 16, v197
	v_mul_f32_e32 v232, 0xbfb8aa3b, v229
	v_exp_f32_e32 v232, v232
	v_mul_f32_e32 v230, v230, v231
	v_add_f32_e32 v232, 1.0, v232
	v_rcp_f32_e32 v232, v232
	s_nop 0
	v_mul_f32_e32 v229, v232, v229
	v_mul_f32_e32 v229, v230, v229
	v_cvt_pk_bf16_f32 v229, v229, s0
	ds_write_b16 v178, v229
	v_max_f32_e32 v229, 0xda24260, v230
	v_rcp_f32_e32 v229, v229
	s_nop 0
	v_mul_f32_e32 v228, v228, v229
	v_cvt_pk_bf16_f32 v228, v228, s0
	ds_write_b16 v178, v228 offset:2304
	v_lshlrev_b32_e32 v228, 16, v220
	v_max_f32_e32 v228, v228, v228
	v_med3_f32 v228, v228, s85, v215
	v_mul_f32_e32 v228, 0xbfb8aa3b, v228
	v_exp_f32_e32 v228, v228
	s_nop 0
	v_add_f32_e32 v229, 1.0, v228
	v_rcp_f32_e32 v229, v229
	v_mul_f32_e32 v228, v158, v228
	v_fma_f32 v231, v158, v229, v137
	v_mul_f32_e32 v228, v228, v229
	v_lshlrev_b32_e32 v229, 16, v199
	v_mul_f32_e32 v232, 0xbfb8aa3b, v229
	v_exp_f32_e32 v232, v232
	v_mul_f32_e32 v230, v230, v231
	v_add_f32_e32 v232, 1.0, v232
	v_rcp_f32_e32 v232, v232
	s_nop 0
	v_mul_f32_e32 v229, v232, v229
	v_mul_f32_e32 v229, v230, v229
	v_cvt_pk_bf16_f32 v229, v229, s0
	ds_write_b16 v179, v229
	v_max_f32_e32 v229, 0xda24260, v230
	v_rcp_f32_e32 v229, v229
	s_nop 0
	v_mul_f32_e32 v228, v228, v229
	v_cvt_pk_bf16_f32 v228, v228, s0
	ds_write_b16 v179, v228 offset:2304
	v_lshlrev_b32_e32 v228, 16, v222
	v_max_f32_e32 v228, v228, v228
	v_med3_f32 v228, v228, s85, v215
	v_mul_f32_e32 v228, 0xbfb8aa3b, v228
	v_exp_f32_e32 v228, v228
	s_nop 0
	v_add_f32_e32 v229, 1.0, v228
	v_rcp_f32_e32 v229, v229
	v_mul_f32_e32 v228, v158, v228
	v_fma_f32 v231, v158, v229, v137
	v_mul_f32_e32 v228, v228, v229
	v_lshlrev_b32_e32 v229, 16, v221
	v_mul_f32_e32 v232, 0xbfb8aa3b, v229
	v_exp_f32_e32 v232, v232
	v_mul_f32_e32 v230, v230, v231
	v_add_f32_e32 v232, 1.0, v232
	v_rcp_f32_e32 v232, v232
	s_nop 0
	v_mul_f32_e32 v229, v232, v229
	v_mul_f32_e32 v229, v230, v229
	v_cvt_pk_bf16_f32 v229, v229, s0
	ds_write_b16 v180, v229
	v_max_f32_e32 v229, 0xda24260, v230
	v_rcp_f32_e32 v229, v229
	s_nop 0
	v_mul_f32_e32 v228, v228, v229
	v_cvt_pk_bf16_f32 v228, v228, s0
	ds_write_b16 v180, v228 offset:2304
	ds_write_b32 v160, v230 offset:6912
